# hyena epilogue 1 split over the wave pair: accumulator halves exchanged through LDS, each wave does two of four row batches
# speedup vs baseline: 1.0043x; 1.0043x over previous
; DI void hyena_item(const P& p, int l, int c, char* smem) {
;     ...
;   if (cwv) hy_conv(acc, abase, U, Zrow, a0, li, g);
;   if (cwv) {
;     const float d1 = p.fbias[(size_t)(l * 2 + 1) * 512 + c];
;     const float x0 = cw[1024 + c], x1 = cw[1536 + 1024 + c], x2 = cw[3072 + 1024 + c], xb = cbias[1024 + c];
;     const u16* rowx = p.hyT + (size_t)(1024 + c) * HYP + bt * SEQ;
;     const u16* rowg = p.hyT + (size_t)(1536 + c) * HYP + bt * SEQ;
;     u16* dst = p.YhT + (size_t)c * HYP + bt * SEQ;
.Lhc1_done:
	v_readlane_b32 s6, v248, 24
	s_nop 1
	s_add_i32 s6, s72, s6
	s_mov_b32 s7, s57
	s_lshl_b64 s[6:7], s[6:7], 2
	s_add_u32 s6, s20, s6
	s_addc_u32 s7, s21, s7
	s_or_b32 s8, s72, 0x400
	s_mov_b32 s9, s57
	s_lshl_b64 s[14:15], s[8:9], 2
	s_add_u32 s76, s28, s14
	s_addc_u32 s77, s29, s15
	v_readlane_b32 s9, v248, 28
	s_nop 1
	s_add_u32 s14, s9, s14
	v_readlane_b32 s9, v248, 29
	s_nop 1
	s_addc_u32 s15, s9, s15
	s_waitcnt lgkmcnt(0)
	s_barrier
	v_and_b32_e32 v249, 0xff, v198
	v_lshlrev_b32_e32 v249, 4, v249
	v_cmp_lt_i32_e32 vcc, 0, v250
	s_cbranch_vccz .Lhy1_xh
	s_nop 15
	ds_write_b128 v249, v[16:19] offset:0
	ds_write_b128 v249, v[20:23] offset:4096
	ds_write_b128 v249, v[24:27] offset:8192
	ds_write_b128 v249, v[28:31] offset:12288
	ds_write_b128 v249, v[0:3] offset:16384
	ds_write_b128 v249, v[4:7] offset:20480
	ds_write_b128 v249, v[8:11] offset:24576
	ds_write_b128 v249, v[12:15] offset:28672
	s_waitcnt lgkmcnt(0)
	s_barrier
	ds_read_b128 v[88:91], v249 offset:32768
	ds_read_b128 v[92:95], v249 offset:36864
	ds_read_b128 v[96:99], v249 offset:40960
	ds_read_b128 v[100:103], v249 offset:45056
	ds_read_b128 v[104:107], v249 offset:49152
	ds_read_b128 v[108:111], v249 offset:53248
	ds_read_b128 v[112:115], v249 offset:57344
	ds_read_b128 v[116:119], v249 offset:61440
	s_waitcnt lgkmcnt(7)
	v_add_f32_e32 v48, v48, v88
	v_add_f32_e32 v49, v49, v89
	v_add_f32_e32 v50, v50, v90
	v_add_f32_e32 v51, v51, v91
	s_waitcnt lgkmcnt(6)
	v_add_f32_e32 v52, v52, v92
	v_add_f32_e32 v53, v53, v93
	v_add_f32_e32 v54, v54, v94
	v_add_f32_e32 v55, v55, v95
	s_waitcnt lgkmcnt(5)
	v_add_f32_e32 v56, v56, v96
	v_add_f32_e32 v57, v57, v97
	v_add_f32_e32 v58, v58, v98
	v_add_f32_e32 v59, v59, v99
	s_waitcnt lgkmcnt(4)
	v_add_f32_e32 v60, v60, v100
	v_add_f32_e32 v61, v61, v101
	v_add_f32_e32 v62, v62, v102
	v_add_f32_e32 v63, v63, v103
	s_waitcnt lgkmcnt(3)
	v_add_f32_e32 v32, v32, v104
	v_add_f32_e32 v33, v33, v105
	v_add_f32_e32 v34, v34, v106
	v_add_f32_e32 v35, v35, v107
	s_waitcnt lgkmcnt(2)
	v_add_f32_e32 v36, v36, v108
	v_add_f32_e32 v37, v37, v109
	v_add_f32_e32 v38, v38, v110
	v_add_f32_e32 v39, v39, v111
	s_waitcnt lgkmcnt(1)
	v_add_f32_e32 v40, v40, v112
	v_add_f32_e32 v41, v41, v113
	v_add_f32_e32 v42, v42, v114
	v_add_f32_e32 v43, v43, v115
	s_waitcnt lgkmcnt(0)
	v_add_f32_e32 v44, v44, v116
	v_add_f32_e32 v45, v45, v117
	v_add_f32_e32 v46, v46, v118
	v_add_f32_e32 v47, v47, v119
	s_branch .Lhy1_xdone
.Lhy1_xh:
	s_nop 15
	ds_write_b128 v249, v[48:51] offset:32768
	ds_write_b128 v249, v[52:55] offset:36864
	ds_write_b128 v249, v[56:59] offset:40960
	ds_write_b128 v249, v[60:63] offset:45056
	ds_write_b128 v249, v[32:35] offset:49152
	ds_write_b128 v249, v[36:39] offset:53248
	ds_write_b128 v249, v[40:43] offset:57344
	ds_write_b128 v249, v[44:47] offset:61440
	s_waitcnt lgkmcnt(0)
	s_barrier
	ds_read_b128 v[88:91], v249 offset:0
	ds_read_b128 v[92:95], v249 offset:4096
	ds_read_b128 v[96:99], v249 offset:8192
	ds_read_b128 v[100:103], v249 offset:12288
	ds_read_b128 v[104:107], v249 offset:16384
	ds_read_b128 v[108:111], v249 offset:20480
	ds_read_b128 v[112:115], v249 offset:24576
	ds_read_b128 v[116:119], v249 offset:28672
	s_waitcnt lgkmcnt(7)
	v_add_f32_e32 v16, v16, v88
	v_add_f32_e32 v17, v17, v89
	v_add_f32_e32 v18, v18, v90
	v_add_f32_e32 v19, v19, v91
	s_waitcnt lgkmcnt(6)
	v_add_f32_e32 v20, v20, v92
	v_add_f32_e32 v21, v21, v93
	v_add_f32_e32 v22, v22, v94
	v_add_f32_e32 v23, v23, v95
	s_waitcnt lgkmcnt(5)
	v_add_f32_e32 v24, v24, v96
	v_add_f32_e32 v25, v25, v97
	v_add_f32_e32 v26, v26, v98
	v_add_f32_e32 v27, v27, v99
	s_waitcnt lgkmcnt(4)
	v_add_f32_e32 v28, v28, v100
	v_add_f32_e32 v29, v29, v101
	v_add_f32_e32 v30, v30, v102
	v_add_f32_e32 v31, v31, v103
	s_waitcnt lgkmcnt(3)
	v_add_f32_e32 v0, v0, v104
	v_add_f32_e32 v1, v1, v105
	v_add_f32_e32 v2, v2, v106
	v_add_f32_e32 v3, v3, v107
	s_waitcnt lgkmcnt(2)
	v_add_f32_e32 v4, v4, v108
	v_add_f32_e32 v5, v5, v109
	v_add_f32_e32 v6, v6, v110
	v_add_f32_e32 v7, v7, v111
	s_waitcnt lgkmcnt(1)
	v_add_f32_e32 v8, v8, v112
	v_add_f32_e32 v9, v9, v113
	v_add_f32_e32 v10, v10, v114
	v_add_f32_e32 v11, v11, v115
	s_waitcnt lgkmcnt(0)
	v_add_f32_e32 v12, v12, v116
	v_add_f32_e32 v13, v13, v117
	v_add_f32_e32 v14, v14, v118
	v_add_f32_e32 v15, v15, v119
; DI float bflo(unsigned v) { return __uint_as_float(v << 16); }
; DI float bfhi(unsigned v) { return __uint_as_float(v & 0xffff0000u); }
; DI float siluf(float x) { return x * __builtin_amdgcn_rcpf(1.f + __expf(-x)); }
; DI void hyena_item(const P& p, int l, int c, char* smem) {
;     ...
;   const float invn0 = 1.0f / (misc[4] + misc[5] + misc[6] + misc[7]);
;   const float invn1 = 1.0f / (misc[8] + misc[9] + misc[10] + misc[11]);
;     ...
; #pragma unroll
;     for (int I = 0; I < 4; ++I)
; #pragma unroll
;       for (int rq = 0; rq < 4; ++rq) {
;         const int bq = 32 * I + 8 * rq + 4 * g;
;         const int t4 = 128 * a + bq;
;         float px[4];
;         sconv4(rowx, t4, x0, x1, x2, xb, px);
;         const uint2 zv = *(const uint2*)(U + (bt * 64 + a) * 136 + bq);
;         const uint2 gv = *(const uint2*)(rowg + t4);
;         const float z1[4] = {bflo(zv.x), bfhi(zv.x), bflo(zv.y), bfhi(zv.y)};
;         const float gt[4] = {bflo(gv.x), bfhi(gv.x), bflo(gv.y), bfhi(gv.y)};
;         float yy[4];
; #pragma unroll
;         for (int j = 0; j < 4; ++j) yy[j] = px[j] * (acc[I][4 * rq + j] * invn1 + z1[j] * d1) * siluf(gt[j]);
;         uint2 ov; ov.x = pack2(yy[0], yy[1]); ov.y = pack2(yy[2], yy[3]);
;         *(uint2*)(dst + t4) = ov;
.Lhy1_xdone:
	global_load_dword v82, v204, s[74:75] offset:2048
	global_load_dword v80, v207, s[74:75]
	global_load_dword v68, v189, s[6:7] offset:2048
	global_load_dword v83, v189, s[76:77]
	global_load_dword v70, v189, s[14:15]
	v_cmp_lt_i32_e32 vcc, 0, v250
	s_cbranch_vccz .Lhy1_eh
	s_or_b32 s98, s72, 0x400
	s_mul_hi_u32 s99, s98, 0x8080
	s_mul_i32 s98, s98, 0x8080
	s_add_u32 s98, s36, s98
	s_addc_u32 s99, s37, s99
	s_add_u32 s98, s98, -4
	s_addc_u32 s99, s99, -1
	s_or_b32 s100, s72, 0x600
	s_mul_hi_u32 s101, s100, 0x8080
	s_mul_i32 s100, s100, 0x8080
	s_add_u32 s100, s36, s100
	s_addc_u32 s101, s37, s101
	s_add_u32 s6, s48, s96
	s_addc_u32 s7, s49, s73
	v_lshl_add_u32 v234, v233, 1, v184
	global_load_dwordx4 v[88:91], v234, s[98:99] offset:0
	global_load_dwordx2 v[92:93], v234, s[100:101] offset:0
	global_load_dwordx4 v[94:97], v234, s[98:99] offset:16
	global_load_dwordx2 v[98:99], v234, s[100:101] offset:16
	global_load_dwordx4 v[100:103], v234, s[98:99] offset:32
	global_load_dwordx2 v[104:105], v234, s[100:101] offset:32
	global_load_dwordx4 v[106:109], v234, s[98:99] offset:48
	global_load_dwordx2 v[110:111], v234, s[100:101] offset:48
	global_load_dwordx4 v[112:115], v234, s[98:99] offset:64
	global_load_dwordx2 v[116:117], v234, s[100:101] offset:64
	global_load_dwordx4 v[118:121], v234, s[98:99] offset:80
	global_load_dwordx2 v[122:123], v234, s[100:101] offset:80
	global_load_dwordx4 v[124:127], v234, s[98:99] offset:96
	global_load_dwordx2 v[128:129], v234, s[100:101] offset:96
	global_load_dwordx4 v[130:133], v234, s[98:99] offset:112
	global_load_dwordx2 v[134:135], v234, s[100:101] offset:112
	v_add_f32_e32 v238, v64, v65
	v_add_f32_e32 v238, v238, v66
	v_add_f32_e32 v238, v238, v67
	v_div_scale_f32 v169, s[8:9], v238, v238, 1.0
	v_rcp_f32_e32 v170, v169
	s_nop 0
	v_fma_f32 v171, -v169, v170, 1.0
	v_fmac_f32_e32 v170, v171, v170
	v_div_scale_f32 v171, vcc, 1.0, v238, 1.0
	v_mul_f32_e32 v236, v171, v170
	v_fma_f32 v237, -v169, v236, v171
	v_fmac_f32_e32 v236, v237, v170
	v_fma_f32 v169, -v169, v236, v171
	v_div_fmas_f32 v169, v169, v170, v236
	v_div_fixup_f32 v238, v169, v238, 1.0
	v_lshl_or_b32 v235, v230, 6, v231
	v_mul_u32_u24_e32 v235, 0x110, v235
	v_lshlrev_b32_e32 v236, 1, v186
	v_add3_u32 v235, s69, v235, v236
	s_waitcnt vmcnt(8)
	ds_read_b64 v[160:161], v235 offset:0
	ds_read_b64 v[162:163], v235 offset:16
	ds_read_b64 v[164:165], v235 offset:32
	ds_read_b64 v[166:167], v235 offset:48
	v_cmp_ne_u32_e32 vcc, 0, v233
	s_nop 1
	v_and_b32_e32 v168, 0xffff0000, v88
	v_cndmask_b32_e32 v168, 0, v168, vcc
	v_lshlrev_b32_e32 v169, 16, v89
	v_and_b32_e32 v170, 0xffff0000, v89
	v_lshlrev_b32_e32 v171, 16, v90
	v_and_b32_e32 v172, 0xffff0000, v90
	v_lshlrev_b32_e32 v173, 16, v91
	v_mul_f32_e32 v178, v83, v168
	v_fmac_f32_e32 v178, v82, v169
	v_fmac_f32_e32 v178, v80, v170
	v_add_f32_e32 v178, v70, v178
	v_mul_f32_e32 v179, v83, v169
	v_fmac_f32_e32 v179, v82, v170
	v_fmac_f32_e32 v179, v80, v171
	v_add_f32_e32 v179, v70, v179
	v_mul_f32_e32 v180, v83, v170
	v_fmac_f32_e32 v180, v82, v171
	v_fmac_f32_e32 v180, v80, v172
	v_add_f32_e32 v180, v70, v180
	v_mul_f32_e32 v181, v83, v171
	v_fmac_f32_e32 v181, v82, v172
	v_fmac_f32_e32 v181, v80, v173
	v_add_f32_e32 v181, v70, v181
	s_waitcnt lgkmcnt(0)
	v_lshlrev_b32_e32 v174, 16, v160
	v_and_b32_e32 v175, 0xffff0000, v160
	v_lshlrev_b32_e32 v176, 16, v161
	v_and_b32_e32 v177, 0xffff0000, v161
	v_mul_f32_e32 v174, v68, v174
	v_mul_f32_e32 v175, v68, v175
	v_mul_f32_e32 v176, v68, v176
	v_mul_f32_e32 v177, v68, v177
	v_fmac_f32_e32 v174, v238, v48
	v_fmac_f32_e32 v175, v238, v49
	v_fmac_f32_e32 v176, v238, v50
	v_fmac_f32_e32 v177, v238, v51
	v_mul_f32_e32 v174, v178, v174
	v_mul_f32_e32 v175, v179, v175
	v_mul_f32_e32 v176, v180, v176
	v_mul_f32_e32 v177, v181, v177
	v_lshlrev_b32_e32 v168, 16, v92
	v_and_b32_e32 v169, 0xffff0000, v92
	v_lshlrev_b32_e32 v170, 16, v93
	v_and_b32_e32 v171, 0xffff0000, v93
	v_mul_f32_e32 v178, 0xbfb8aa3b, v168
	v_mul_f32_e32 v179, 0xbfb8aa3b, v169
	v_mul_f32_e32 v180, 0xbfb8aa3b, v170
	v_mul_f32_e32 v181, 0xbfb8aa3b, v171
	v_exp_f32_e32 v178, v178
	v_exp_f32_e32 v179, v179
	v_exp_f32_e32 v180, v180
	v_exp_f32_e32 v181, v181
	v_add_f32_e32 v178, 1.0, v178
	v_add_f32_e32 v179, 1.0, v179
	v_add_f32_e32 v180, 1.0, v180
	v_add_f32_e32 v181, 1.0, v181
	v_rcp_f32_e32 v178, v178
	v_rcp_f32_e32 v179, v179
	v_rcp_f32_e32 v180, v180
	v_rcp_f32_e32 v181, v181
	v_mul_f32_e32 v178, v178, v168
	v_mul_f32_e32 v179, v179, v169
	v_mul_f32_e32 v180, v180, v170
	v_mul_f32_e32 v181, v181, v171
	v_mul_f32_e32 v174, v174, v178
	v_mul_f32_e32 v175, v175, v179
	v_mul_f32_e32 v176, v176, v180
	v_mul_f32_e32 v177, v177, v181
	v_cvt_pk_bf16_f32 v182, v174, v175
	v_cvt_pk_bf16_f32 v183, v176, v177
	global_store_dwordx2 v234, v[182:183], s[6:7] offset:0
	v_and_b32_e32 v168, 0xffff0000, v94
	v_lshlrev_b32_e32 v169, 16, v95
	v_and_b32_e32 v170, 0xffff0000, v95
	v_lshlrev_b32_e32 v171, 16, v96
	v_and_b32_e32 v172, 0xffff0000, v96
	v_lshlrev_b32_e32 v173, 16, v97
	v_mul_f32_e32 v178, v83, v168
	v_fmac_f32_e32 v178, v82, v169
	v_fmac_f32_e32 v178, v80, v170
	v_add_f32_e32 v178, v70, v178
	v_mul_f32_e32 v179, v83, v169
	v_fmac_f32_e32 v179, v82, v170
	v_fmac_f32_e32 v179, v80, v171
	v_add_f32_e32 v179, v70, v179
	v_mul_f32_e32 v180, v83, v170
	v_fmac_f32_e32 v180, v82, v171
	v_fmac_f32_e32 v180, v80, v172
	v_add_f32_e32 v180, v70, v180
	v_mul_f32_e32 v181, v83, v171
	v_fmac_f32_e32 v181, v82, v172
	v_fmac_f32_e32 v181, v80, v173
	v_add_f32_e32 v181, v70, v181
	v_lshlrev_b32_e32 v174, 16, v162
	v_and_b32_e32 v175, 0xffff0000, v162
	v_lshlrev_b32_e32 v176, 16, v163
	v_and_b32_e32 v177, 0xffff0000, v163
; DI float bflo(unsigned v) { return __uint_as_float(v << 16); }
; DI float bfhi(unsigned v) { return __uint_as_float(v & 0xffff0000u); }
; DI float siluf(float x) { return x * __builtin_amdgcn_rcpf(1.f + __expf(-x)); }
; DI void hyena_item(const P& p, int l, int c, char* smem) {
;     ...
;       for (int rq = 0; rq < 4; ++rq) {
;         const int bq = 32 * I + 8 * rq + 4 * g;
;         const int t4 = 128 * a + bq;
;         float px[4];
;         sconv4(rowx, t4, x0, x1, x2, xb, px);
;         const uint2 zv = *(const uint2*)(U + (bt * 64 + a) * 136 + bq);
;         const uint2 gv = *(const uint2*)(rowg + t4);
;         const float z1[4] = {bflo(zv.x), bfhi(zv.x), bflo(zv.y), bfhi(zv.y)};
;         const float gt[4] = {bflo(gv.x), bfhi(gv.x), bflo(gv.y), bfhi(gv.y)};
;         float yy[4];
; #pragma unroll
;         for (int j = 0; j < 4; ++j) yy[j] = px[j] * (acc[I][4 * rq + j] * invn1 + z1[j] * d1) * siluf(gt[j]);
;         uint2 ov; ov.x = pack2(yy[0], yy[1]); ov.y = pack2(yy[2], yy[3]);
;         *(uint2*)(dst + t4) = ov;
	v_mul_f32_e32 v174, v68, v174
	v_mul_f32_e32 v175, v68, v175
	v_mul_f32_e32 v176, v68, v176
	v_mul_f32_e32 v177, v68, v177
	v_fmac_f32_e32 v174, v238, v52
	v_fmac_f32_e32 v175, v238, v53
	v_fmac_f32_e32 v176, v238, v54
	v_fmac_f32_e32 v177, v238, v55
	v_mul_f32_e32 v174, v178, v174
	v_mul_f32_e32 v175, v179, v175
	v_mul_f32_e32 v176, v180, v176
	v_mul_f32_e32 v177, v181, v177
	v_lshlrev_b32_e32 v168, 16, v98
	v_and_b32_e32 v169, 0xffff0000, v98
	v_lshlrev_b32_e32 v170, 16, v99
	v_and_b32_e32 v171, 0xffff0000, v99
	v_mul_f32_e32 v178, 0xbfb8aa3b, v168
	v_mul_f32_e32 v179, 0xbfb8aa3b, v169
	v_mul_f32_e32 v180, 0xbfb8aa3b, v170
	v_mul_f32_e32 v181, 0xbfb8aa3b, v171
	v_exp_f32_e32 v178, v178
	v_exp_f32_e32 v179, v179
	v_exp_f32_e32 v180, v180
	v_exp_f32_e32 v181, v181
	v_add_f32_e32 v178, 1.0, v178
	v_add_f32_e32 v179, 1.0, v179
	v_add_f32_e32 v180, 1.0, v180
	v_add_f32_e32 v181, 1.0, v181
	v_rcp_f32_e32 v178, v178
	v_rcp_f32_e32 v179, v179
	v_rcp_f32_e32 v180, v180
	v_rcp_f32_e32 v181, v181
	v_mul_f32_e32 v178, v178, v168
	v_mul_f32_e32 v179, v179, v169
	v_mul_f32_e32 v180, v180, v170
	v_mul_f32_e32 v181, v181, v171
	v_mul_f32_e32 v174, v174, v178
	v_mul_f32_e32 v175, v175, v179
	v_mul_f32_e32 v176, v176, v180
	v_mul_f32_e32 v177, v177, v181
	v_cvt_pk_bf16_f32 v182, v174, v175
	v_cvt_pk_bf16_f32 v183, v176, v177
	global_store_dwordx2 v234, v[182:183], s[6:7] offset:16
	v_and_b32_e32 v168, 0xffff0000, v100
	v_lshlrev_b32_e32 v169, 16, v101
	v_and_b32_e32 v170, 0xffff0000, v101
	v_lshlrev_b32_e32 v171, 16, v102
	v_and_b32_e32 v172, 0xffff0000, v102
	v_lshlrev_b32_e32 v173, 16, v103
	v_mul_f32_e32 v178, v83, v168
	v_fmac_f32_e32 v178, v82, v169
	v_fmac_f32_e32 v178, v80, v170
	v_add_f32_e32 v178, v70, v178
	v_mul_f32_e32 v179, v83, v169
	v_fmac_f32_e32 v179, v82, v170
	v_fmac_f32_e32 v179, v80, v171
	v_add_f32_e32 v179, v70, v179
	v_mul_f32_e32 v180, v83, v170
	v_fmac_f32_e32 v180, v82, v171
	v_fmac_f32_e32 v180, v80, v172
	v_add_f32_e32 v180, v70, v180
	v_mul_f32_e32 v181, v83, v171
	v_fmac_f32_e32 v181, v82, v172
	v_fmac_f32_e32 v181, v80, v173
	v_add_f32_e32 v181, v70, v181
	v_lshlrev_b32_e32 v174, 16, v164
	v_and_b32_e32 v175, 0xffff0000, v164
	v_lshlrev_b32_e32 v176, 16, v165
	v_and_b32_e32 v177, 0xffff0000, v165
	v_mul_f32_e32 v174, v68, v174
	v_mul_f32_e32 v175, v68, v175
	v_mul_f32_e32 v176, v68, v176
	v_mul_f32_e32 v177, v68, v177
	v_fmac_f32_e32 v174, v238, v56
	v_fmac_f32_e32 v175, v238, v57
	v_fmac_f32_e32 v176, v238, v58
	v_fmac_f32_e32 v177, v238, v59
	v_mul_f32_e32 v174, v178, v174
	v_mul_f32_e32 v175, v179, v175
	v_mul_f32_e32 v176, v180, v176
	v_mul_f32_e32 v177, v181, v177
	v_lshlrev_b32_e32 v168, 16, v104
	v_and_b32_e32 v169, 0xffff0000, v104
	v_lshlrev_b32_e32 v170, 16, v105
	v_and_b32_e32 v171, 0xffff0000, v105
	v_mul_f32_e32 v178, 0xbfb8aa3b, v168
	v_mul_f32_e32 v179, 0xbfb8aa3b, v169
	v_mul_f32_e32 v180, 0xbfb8aa3b, v170
	v_mul_f32_e32 v181, 0xbfb8aa3b, v171
	v_exp_f32_e32 v178, v178
	v_exp_f32_e32 v179, v179
	v_exp_f32_e32 v180, v180
	v_exp_f32_e32 v181, v181
	v_add_f32_e32 v178, 1.0, v178
	v_add_f32_e32 v179, 1.0, v179
	v_add_f32_e32 v180, 1.0, v180
	v_add_f32_e32 v181, 1.0, v181
	v_rcp_f32_e32 v178, v178
	v_rcp_f32_e32 v179, v179
	v_rcp_f32_e32 v180, v180
	v_rcp_f32_e32 v181, v181
	v_mul_f32_e32 v178, v178, v168
	v_mul_f32_e32 v179, v179, v169
	v_mul_f32_e32 v180, v180, v170
	v_mul_f32_e32 v181, v181, v171
	v_mul_f32_e32 v174, v174, v178
	v_mul_f32_e32 v175, v175, v179
	v_mul_f32_e32 v176, v176, v180
	v_mul_f32_e32 v177, v177, v181
	v_cvt_pk_bf16_f32 v182, v174, v175
	v_cvt_pk_bf16_f32 v183, v176, v177
	global_store_dwordx2 v234, v[182:183], s[6:7] offset:32
	v_and_b32_e32 v168, 0xffff0000, v106
	v_lshlrev_b32_e32 v169, 16, v107
	v_and_b32_e32 v170, 0xffff0000, v107
	v_lshlrev_b32_e32 v171, 16, v108
	v_and_b32_e32 v172, 0xffff0000, v108
	v_lshlrev_b32_e32 v173, 16, v109
	v_mul_f32_e32 v178, v83, v168
	v_fmac_f32_e32 v178, v82, v169
	v_fmac_f32_e32 v178, v80, v170
	v_add_f32_e32 v178, v70, v178
	v_mul_f32_e32 v179, v83, v169
	v_fmac_f32_e32 v179, v82, v170
	v_fmac_f32_e32 v179, v80, v171
	v_add_f32_e32 v179, v70, v179
	v_mul_f32_e32 v180, v83, v170
	v_fmac_f32_e32 v180, v82, v171
	v_fmac_f32_e32 v180, v80, v172
	v_add_f32_e32 v180, v70, v180
	v_mul_f32_e32 v181, v83, v171
	v_fmac_f32_e32 v181, v82, v172
	v_fmac_f32_e32 v181, v80, v173
	v_add_f32_e32 v181, v70, v181
	v_lshlrev_b32_e32 v174, 16, v166
	v_and_b32_e32 v175, 0xffff0000, v166
	v_lshlrev_b32_e32 v176, 16, v167
	v_and_b32_e32 v177, 0xffff0000, v167
	v_mul_f32_e32 v174, v68, v174
	v_mul_f32_e32 v175, v68, v175
	v_mul_f32_e32 v176, v68, v176
	v_mul_f32_e32 v177, v68, v177
	v_fmac_f32_e32 v174, v238, v60
	v_fmac_f32_e32 v175, v238, v61
	v_fmac_f32_e32 v176, v238, v62
	v_fmac_f32_e32 v177, v238, v63
	v_mul_f32_e32 v174, v178, v174
	v_mul_f32_e32 v175, v179, v175
	v_mul_f32_e32 v176, v180, v176
	v_mul_f32_e32 v177, v181, v177
	v_lshlrev_b32_e32 v168, 16, v110
	v_and_b32_e32 v169, 0xffff0000, v110
	v_lshlrev_b32_e32 v170, 16, v111
	v_and_b32_e32 v171, 0xffff0000, v111
	v_mul_f32_e32 v178, 0xbfb8aa3b, v168
	v_mul_f32_e32 v179, 0xbfb8aa3b, v169
	v_mul_f32_e32 v180, 0xbfb8aa3b, v170
	v_mul_f32_e32 v181, 0xbfb8aa3b, v171
	v_exp_f32_e32 v178, v178
	v_exp_f32_e32 v179, v179
	v_exp_f32_e32 v180, v180
	v_exp_f32_e32 v181, v181
	v_add_f32_e32 v178, 1.0, v178
	v_add_f32_e32 v179, 1.0, v179
	v_add_f32_e32 v180, 1.0, v180
	v_add_f32_e32 v181, 1.0, v181
	v_rcp_f32_e32 v178, v178
	v_rcp_f32_e32 v179, v179
	v_rcp_f32_e32 v180, v180
	v_rcp_f32_e32 v181, v181
	v_mul_f32_e32 v178, v178, v168
	v_mul_f32_e32 v179, v179, v169
	v_mul_f32_e32 v180, v180, v170
	v_mul_f32_e32 v181, v181, v171
	v_mul_f32_e32 v174, v174, v178
	v_mul_f32_e32 v175, v175, v179
	v_mul_f32_e32 v176, v176, v180
	v_mul_f32_e32 v177, v177, v181
	v_cvt_pk_bf16_f32 v182, v174, v175
	v_cvt_pk_bf16_f32 v183, v176, v177
	global_store_dwordx2 v234, v[182:183], s[6:7] offset:48
	s_waitcnt vmcnt(4)
; DI float bflo(unsigned v) { return __uint_as_float(v << 16); }
; DI float bfhi(unsigned v) { return __uint_as_float(v & 0xffff0000u); }
; DI float siluf(float x) { return x * __builtin_amdgcn_rcpf(1.f + __expf(-x)); }
; DI void hyena_item(const P& p, int l, int c, char* smem) {
;     ...
;       for (int rq = 0; rq < 4; ++rq) {
;         const int bq = 32 * I + 8 * rq + 4 * g;
;         const int t4 = 128 * a + bq;
;         float px[4];
;         sconv4(rowx, t4, x0, x1, x2, xb, px);
;         const uint2 zv = *(const uint2*)(U + (bt * 64 + a) * 136 + bq);
;         const uint2 gv = *(const uint2*)(rowg + t4);
;         const float z1[4] = {bflo(zv.x), bfhi(zv.x), bflo(zv.y), bfhi(zv.y)};
;         const float gt[4] = {bflo(gv.x), bfhi(gv.x), bflo(gv.y), bfhi(gv.y)};
;         float yy[4];
; #pragma unroll
;         for (int j = 0; j < 4; ++j) yy[j] = px[j] * (acc[I][4 * rq + j] * invn1 + z1[j] * d1) * siluf(gt[j]);
;         uint2 ov; ov.x = pack2(yy[0], yy[1]); ov.y = pack2(yy[2], yy[3]);
;         *(uint2*)(dst + t4) = ov;
	ds_read_b64 v[160:161], v235 offset:64
	ds_read_b64 v[162:163], v235 offset:80
	ds_read_b64 v[164:165], v235 offset:96
	ds_read_b64 v[166:167], v235 offset:112
	v_and_b32_e32 v168, 0xffff0000, v112
	v_lshlrev_b32_e32 v169, 16, v113
	v_and_b32_e32 v170, 0xffff0000, v113
	v_lshlrev_b32_e32 v171, 16, v114
	v_and_b32_e32 v172, 0xffff0000, v114
	v_lshlrev_b32_e32 v173, 16, v115
	v_mul_f32_e32 v178, v83, v168
	v_fmac_f32_e32 v178, v82, v169
	v_fmac_f32_e32 v178, v80, v170
	v_add_f32_e32 v178, v70, v178
	v_mul_f32_e32 v179, v83, v169
	v_fmac_f32_e32 v179, v82, v170
	v_fmac_f32_e32 v179, v80, v171
	v_add_f32_e32 v179, v70, v179
	v_mul_f32_e32 v180, v83, v170
	v_fmac_f32_e32 v180, v82, v171
	v_fmac_f32_e32 v180, v80, v172
	v_add_f32_e32 v180, v70, v180
	v_mul_f32_e32 v181, v83, v171
	v_fmac_f32_e32 v181, v82, v172
	v_fmac_f32_e32 v181, v80, v173
	v_add_f32_e32 v181, v70, v181
	s_waitcnt lgkmcnt(0)
	v_lshlrev_b32_e32 v174, 16, v160
	v_and_b32_e32 v175, 0xffff0000, v160
	v_lshlrev_b32_e32 v176, 16, v161
	v_and_b32_e32 v177, 0xffff0000, v161
	v_mul_f32_e32 v174, v68, v174
	v_mul_f32_e32 v175, v68, v175
	v_mul_f32_e32 v176, v68, v176
	v_mul_f32_e32 v177, v68, v177
	v_fmac_f32_e32 v174, v238, v32
	v_fmac_f32_e32 v175, v238, v33
	v_fmac_f32_e32 v176, v238, v34
	v_fmac_f32_e32 v177, v238, v35
	v_mul_f32_e32 v174, v178, v174
	v_mul_f32_e32 v175, v179, v175
	v_mul_f32_e32 v176, v180, v176
	v_mul_f32_e32 v177, v181, v177
	v_lshlrev_b32_e32 v168, 16, v116
	v_and_b32_e32 v169, 0xffff0000, v116
	v_lshlrev_b32_e32 v170, 16, v117
	v_and_b32_e32 v171, 0xffff0000, v117
	v_mul_f32_e32 v178, 0xbfb8aa3b, v168
	v_mul_f32_e32 v179, 0xbfb8aa3b, v169
	v_mul_f32_e32 v180, 0xbfb8aa3b, v170
	v_mul_f32_e32 v181, 0xbfb8aa3b, v171
	v_exp_f32_e32 v178, v178
	v_exp_f32_e32 v179, v179
	v_exp_f32_e32 v180, v180
	v_exp_f32_e32 v181, v181
	v_add_f32_e32 v178, 1.0, v178
	v_add_f32_e32 v179, 1.0, v179
	v_add_f32_e32 v180, 1.0, v180
	v_add_f32_e32 v181, 1.0, v181
	v_rcp_f32_e32 v178, v178
	v_rcp_f32_e32 v179, v179
	v_rcp_f32_e32 v180, v180
	v_rcp_f32_e32 v181, v181
	v_mul_f32_e32 v178, v178, v168
	v_mul_f32_e32 v179, v179, v169
	v_mul_f32_e32 v180, v180, v170
	v_mul_f32_e32 v181, v181, v171
	v_mul_f32_e32 v174, v174, v178
	v_mul_f32_e32 v175, v175, v179
	v_mul_f32_e32 v176, v176, v180
	v_mul_f32_e32 v177, v177, v181
	v_cvt_pk_bf16_f32 v182, v174, v175
	v_cvt_pk_bf16_f32 v183, v176, v177
	global_store_dwordx2 v234, v[182:183], s[6:7] offset:64
	v_and_b32_e32 v168, 0xffff0000, v118
	v_lshlrev_b32_e32 v169, 16, v119
	v_and_b32_e32 v170, 0xffff0000, v119
	v_lshlrev_b32_e32 v171, 16, v120
	v_and_b32_e32 v172, 0xffff0000, v120
	v_lshlrev_b32_e32 v173, 16, v121
	v_mul_f32_e32 v178, v83, v168
	v_fmac_f32_e32 v178, v82, v169
	v_fmac_f32_e32 v178, v80, v170
	v_add_f32_e32 v178, v70, v178
	v_mul_f32_e32 v179, v83, v169
	v_fmac_f32_e32 v179, v82, v170
	v_fmac_f32_e32 v179, v80, v171
	v_add_f32_e32 v179, v70, v179
	v_mul_f32_e32 v180, v83, v170
	v_fmac_f32_e32 v180, v82, v171
	v_fmac_f32_e32 v180, v80, v172
	v_add_f32_e32 v180, v70, v180
	v_mul_f32_e32 v181, v83, v171
	v_fmac_f32_e32 v181, v82, v172
	v_fmac_f32_e32 v181, v80, v173
	v_add_f32_e32 v181, v70, v181
	v_lshlrev_b32_e32 v174, 16, v162
	v_and_b32_e32 v175, 0xffff0000, v162
	v_lshlrev_b32_e32 v176, 16, v163
	v_and_b32_e32 v177, 0xffff0000, v163
	v_mul_f32_e32 v174, v68, v174
	v_mul_f32_e32 v175, v68, v175
	v_mul_f32_e32 v176, v68, v176
	v_mul_f32_e32 v177, v68, v177
	v_fmac_f32_e32 v174, v238, v36
	v_fmac_f32_e32 v175, v238, v37
	v_fmac_f32_e32 v176, v238, v38
	v_fmac_f32_e32 v177, v238, v39
	v_mul_f32_e32 v174, v178, v174
	v_mul_f32_e32 v175, v179, v175
	v_mul_f32_e32 v176, v180, v176
	v_mul_f32_e32 v177, v181, v177
	v_lshlrev_b32_e32 v168, 16, v122
	v_and_b32_e32 v169, 0xffff0000, v122
	v_lshlrev_b32_e32 v170, 16, v123
	v_and_b32_e32 v171, 0xffff0000, v123
	v_mul_f32_e32 v178, 0xbfb8aa3b, v168
	v_mul_f32_e32 v179, 0xbfb8aa3b, v169
	v_mul_f32_e32 v180, 0xbfb8aa3b, v170
	v_mul_f32_e32 v181, 0xbfb8aa3b, v171
	v_exp_f32_e32 v178, v178
	v_exp_f32_e32 v179, v179
	v_exp_f32_e32 v180, v180
	v_exp_f32_e32 v181, v181
	v_add_f32_e32 v178, 1.0, v178
	v_add_f32_e32 v179, 1.0, v179
	v_add_f32_e32 v180, 1.0, v180
	v_add_f32_e32 v181, 1.0, v181
	v_rcp_f32_e32 v178, v178
	v_rcp_f32_e32 v179, v179
	v_rcp_f32_e32 v180, v180
	v_rcp_f32_e32 v181, v181
	v_mul_f32_e32 v178, v178, v168
	v_mul_f32_e32 v179, v179, v169
	v_mul_f32_e32 v180, v180, v170
	v_mul_f32_e32 v181, v181, v171
	v_mul_f32_e32 v174, v174, v178
	v_mul_f32_e32 v175, v175, v179
	v_mul_f32_e32 v176, v176, v180
	v_mul_f32_e32 v177, v177, v181
	v_cvt_pk_bf16_f32 v182, v174, v175
	v_cvt_pk_bf16_f32 v183, v176, v177
	global_store_dwordx2 v234, v[182:183], s[6:7] offset:80
	v_and_b32_e32 v168, 0xffff0000, v124
	v_lshlrev_b32_e32 v169, 16, v125
	v_and_b32_e32 v170, 0xffff0000, v125
	v_lshlrev_b32_e32 v171, 16, v126
	v_and_b32_e32 v172, 0xffff0000, v126
	v_lshlrev_b32_e32 v173, 16, v127
	v_mul_f32_e32 v178, v83, v168
	v_fmac_f32_e32 v178, v82, v169
	v_fmac_f32_e32 v178, v80, v170
	v_add_f32_e32 v178, v70, v178
	v_mul_f32_e32 v179, v83, v169
	v_fmac_f32_e32 v179, v82, v170
	v_fmac_f32_e32 v179, v80, v171
	v_add_f32_e32 v179, v70, v179
	v_mul_f32_e32 v180, v83, v170
	v_fmac_f32_e32 v180, v82, v171
	v_fmac_f32_e32 v180, v80, v172
	v_add_f32_e32 v180, v70, v180
	v_mul_f32_e32 v181, v83, v171
	v_fmac_f32_e32 v181, v82, v172
	v_fmac_f32_e32 v181, v80, v173
	v_add_f32_e32 v181, v70, v181
	v_lshlrev_b32_e32 v174, 16, v164
	v_and_b32_e32 v175, 0xffff0000, v164
	v_lshlrev_b32_e32 v176, 16, v165
	v_and_b32_e32 v177, 0xffff0000, v165
	v_mul_f32_e32 v174, v68, v174
	v_mul_f32_e32 v175, v68, v175
	v_mul_f32_e32 v176, v68, v176
; DI float bflo(unsigned v) { return __uint_as_float(v << 16); }
; DI float bfhi(unsigned v) { return __uint_as_float(v & 0xffff0000u); }
; DI float siluf(float x) { return x * __builtin_amdgcn_rcpf(1.f + __expf(-x)); }
; DI void hyena_item(const P& p, int l, int c, char* smem) {
;     ...
;   const float invn0 = 1.0f / (misc[4] + misc[5] + misc[6] + misc[7]);
;   const float invn1 = 1.0f / (misc[8] + misc[9] + misc[10] + misc[11]);
;     ...
; #pragma unroll
;     for (int I = 0; I < 4; ++I)
; #pragma unroll
;       for (int rq = 0; rq < 4; ++rq) {
;         const int bq = 32 * I + 8 * rq + 4 * g;
;         const int t4 = 128 * a + bq;
;         float px[4];
;         sconv4(rowx, t4, x0, x1, x2, xb, px);
;         const uint2 zv = *(const uint2*)(U + (bt * 64 + a) * 136 + bq);
;         const uint2 gv = *(const uint2*)(rowg + t4);
;         const float z1[4] = {bflo(zv.x), bfhi(zv.x), bflo(zv.y), bfhi(zv.y)};
;         const float gt[4] = {bflo(gv.x), bfhi(gv.x), bflo(gv.y), bfhi(gv.y)};
;         float yy[4];
; #pragma unroll
;         for (int j = 0; j < 4; ++j) yy[j] = px[j] * (acc[I][4 * rq + j] * invn1 + z1[j] * d1) * siluf(gt[j]);
;         uint2 ov; ov.x = pack2(yy[0], yy[1]); ov.y = pack2(yy[2], yy[3]);
;         *(uint2*)(dst + t4) = ov;
	v_mul_f32_e32 v177, v68, v177
	v_fmac_f32_e32 v174, v238, v40
	v_fmac_f32_e32 v175, v238, v41
	v_fmac_f32_e32 v176, v238, v42
	v_fmac_f32_e32 v177, v238, v43
	v_mul_f32_e32 v174, v178, v174
	v_mul_f32_e32 v175, v179, v175
	v_mul_f32_e32 v176, v180, v176
	v_mul_f32_e32 v177, v181, v177
	v_lshlrev_b32_e32 v168, 16, v128
	v_and_b32_e32 v169, 0xffff0000, v128
	v_lshlrev_b32_e32 v170, 16, v129
	v_and_b32_e32 v171, 0xffff0000, v129
	v_mul_f32_e32 v178, 0xbfb8aa3b, v168
	v_mul_f32_e32 v179, 0xbfb8aa3b, v169
	v_mul_f32_e32 v180, 0xbfb8aa3b, v170
	v_mul_f32_e32 v181, 0xbfb8aa3b, v171
	v_exp_f32_e32 v178, v178
	v_exp_f32_e32 v179, v179
	v_exp_f32_e32 v180, v180
	v_exp_f32_e32 v181, v181
	v_add_f32_e32 v178, 1.0, v178
	v_add_f32_e32 v179, 1.0, v179
	v_add_f32_e32 v180, 1.0, v180
	v_add_f32_e32 v181, 1.0, v181
	v_rcp_f32_e32 v178, v178
	v_rcp_f32_e32 v179, v179
	v_rcp_f32_e32 v180, v180
	v_rcp_f32_e32 v181, v181
	v_mul_f32_e32 v178, v178, v168
	v_mul_f32_e32 v179, v179, v169
	v_mul_f32_e32 v180, v180, v170
	v_mul_f32_e32 v181, v181, v171
	v_mul_f32_e32 v174, v174, v178
	v_mul_f32_e32 v175, v175, v179
	v_mul_f32_e32 v176, v176, v180
	v_mul_f32_e32 v177, v177, v181
	v_cvt_pk_bf16_f32 v182, v174, v175
	v_cvt_pk_bf16_f32 v183, v176, v177
	global_store_dwordx2 v234, v[182:183], s[6:7] offset:96
	v_and_b32_e32 v168, 0xffff0000, v130
	v_lshlrev_b32_e32 v169, 16, v131
	v_and_b32_e32 v170, 0xffff0000, v131
	v_lshlrev_b32_e32 v171, 16, v132
	v_and_b32_e32 v172, 0xffff0000, v132
	v_lshlrev_b32_e32 v173, 16, v133
	v_mul_f32_e32 v178, v83, v168
	v_fmac_f32_e32 v178, v82, v169
	v_fmac_f32_e32 v178, v80, v170
	v_add_f32_e32 v178, v70, v178
	v_mul_f32_e32 v179, v83, v169
	v_fmac_f32_e32 v179, v82, v170
	v_fmac_f32_e32 v179, v80, v171
	v_add_f32_e32 v179, v70, v179
	v_mul_f32_e32 v180, v83, v170
	v_fmac_f32_e32 v180, v82, v171
	v_fmac_f32_e32 v180, v80, v172
	v_add_f32_e32 v180, v70, v180
	v_mul_f32_e32 v181, v83, v171
	v_fmac_f32_e32 v181, v82, v172
	v_fmac_f32_e32 v181, v80, v173
	v_add_f32_e32 v181, v70, v181
	v_lshlrev_b32_e32 v174, 16, v166
	v_and_b32_e32 v175, 0xffff0000, v166
	v_lshlrev_b32_e32 v176, 16, v167
	v_and_b32_e32 v177, 0xffff0000, v167
	v_mul_f32_e32 v174, v68, v174
	v_mul_f32_e32 v175, v68, v175
	v_mul_f32_e32 v176, v68, v176
	v_mul_f32_e32 v177, v68, v177
	v_fmac_f32_e32 v174, v238, v44
	v_fmac_f32_e32 v175, v238, v45
	v_fmac_f32_e32 v176, v238, v46
	v_fmac_f32_e32 v177, v238, v47
	v_mul_f32_e32 v174, v178, v174
	v_mul_f32_e32 v175, v179, v175
	v_mul_f32_e32 v176, v180, v176
	v_mul_f32_e32 v177, v181, v177
	v_lshlrev_b32_e32 v168, 16, v134
	v_and_b32_e32 v169, 0xffff0000, v134
	v_lshlrev_b32_e32 v170, 16, v135
	v_and_b32_e32 v171, 0xffff0000, v135
	v_mul_f32_e32 v178, 0xbfb8aa3b, v168
	v_mul_f32_e32 v179, 0xbfb8aa3b, v169
	v_mul_f32_e32 v180, 0xbfb8aa3b, v170
	v_mul_f32_e32 v181, 0xbfb8aa3b, v171
	v_exp_f32_e32 v178, v178
	v_exp_f32_e32 v179, v179
	v_exp_f32_e32 v180, v180
	v_exp_f32_e32 v181, v181
	v_add_f32_e32 v178, 1.0, v178
	v_add_f32_e32 v179, 1.0, v179
	v_add_f32_e32 v180, 1.0, v180
	v_add_f32_e32 v181, 1.0, v181
	v_rcp_f32_e32 v178, v178
	v_rcp_f32_e32 v179, v179
	v_rcp_f32_e32 v180, v180
	v_rcp_f32_e32 v181, v181
	v_mul_f32_e32 v178, v178, v168
	v_mul_f32_e32 v179, v179, v169
	v_mul_f32_e32 v180, v180, v170
	v_mul_f32_e32 v181, v181, v171
	v_mul_f32_e32 v174, v174, v178
	v_mul_f32_e32 v175, v175, v179
	v_mul_f32_e32 v176, v176, v180
	v_mul_f32_e32 v177, v177, v181
	v_cvt_pk_bf16_f32 v182, v174, v175
	v_cvt_pk_bf16_f32 v183, v176, v177
	global_store_dwordx2 v234, v[182:183], s[6:7] offset:112
	s_branch .Lhy1_skip
.Lhy1_eh:
	s_or_b32 s98, s72, 0x400
	s_mul_hi_u32 s99, s98, 0x8080
	s_mul_i32 s98, s98, 0x8080
	s_add_u32 s98, s36, s98
	s_addc_u32 s99, s37, s99
	s_add_u32 s98, s98, -4
	s_addc_u32 s99, s99, -1
	s_or_b32 s100, s72, 0x600
	s_mul_hi_u32 s101, s100, 0x8080
	s_mul_i32 s100, s100, 0x8080
	s_add_u32 s100, s36, s100
	s_addc_u32 s101, s37, s101
	s_add_u32 s6, s48, s96
	s_addc_u32 s7, s49, s73
	v_lshl_add_u32 v234, v233, 1, v184
	global_load_dwordx4 v[88:91], v234, s[98:99] offset:128
	global_load_dwordx2 v[92:93], v234, s[100:101] offset:128
	global_load_dwordx4 v[94:97], v234, s[98:99] offset:144
	global_load_dwordx2 v[98:99], v234, s[100:101] offset:144
	global_load_dwordx4 v[100:103], v234, s[98:99] offset:160
	global_load_dwordx2 v[104:105], v234, s[100:101] offset:160
	global_load_dwordx4 v[106:109], v234, s[98:99] offset:176
	global_load_dwordx2 v[110:111], v234, s[100:101] offset:176
	global_load_dwordx4 v[112:115], v234, s[98:99] offset:192
	global_load_dwordx2 v[116:117], v234, s[100:101] offset:192
	global_load_dwordx4 v[118:121], v234, s[98:99] offset:208
	global_load_dwordx2 v[122:123], v234, s[100:101] offset:208
	global_load_dwordx4 v[124:127], v234, s[98:99] offset:224
	global_load_dwordx2 v[128:129], v234, s[100:101] offset:224
	global_load_dwordx4 v[130:133], v234, s[98:99] offset:240
	global_load_dwordx2 v[134:135], v234, s[100:101] offset:240
	v_add_f32_e32 v238, v64, v65
	v_add_f32_e32 v238, v238, v66
	v_add_f32_e32 v238, v238, v67
	v_div_scale_f32 v169, s[8:9], v238, v238, 1.0
	v_rcp_f32_e32 v170, v169
	s_nop 0
	v_fma_f32 v171, -v169, v170, 1.0
	v_fmac_f32_e32 v170, v171, v170
	v_div_scale_f32 v171, vcc, 1.0, v238, 1.0
	v_mul_f32_e32 v236, v171, v170
	v_fma_f32 v237, -v169, v236, v171
	v_fmac_f32_e32 v236, v237, v170
	v_fma_f32 v169, -v169, v236, v171
	v_div_fmas_f32 v169, v169, v170, v236
	v_div_fixup_f32 v238, v169, v238, 1.0
	v_lshl_or_b32 v235, v230, 6, v231
	v_mul_u32_u24_e32 v235, 0x110, v235
	v_lshlrev_b32_e32 v236, 1, v186
	v_add3_u32 v235, s69, v235, v236
	s_waitcnt vmcnt(8)
; DI float bflo(unsigned v) { return __uint_as_float(v << 16); }
; DI float bfhi(unsigned v) { return __uint_as_float(v & 0xffff0000u); }
; DI float siluf(float x) { return x * __builtin_amdgcn_rcpf(1.f + __expf(-x)); }
; DI void hyena_item(const P& p, int l, int c, char* smem) {
;     ...
;       for (int rq = 0; rq < 4; ++rq) {
;         const int bq = 32 * I + 8 * rq + 4 * g;
;         const int t4 = 128 * a + bq;
;         float px[4];
;         sconv4(rowx, t4, x0, x1, x2, xb, px);
;         const uint2 zv = *(const uint2*)(U + (bt * 64 + a) * 136 + bq);
;         const uint2 gv = *(const uint2*)(rowg + t4);
;         const float z1[4] = {bflo(zv.x), bfhi(zv.x), bflo(zv.y), bfhi(zv.y)};
;         const float gt[4] = {bflo(gv.x), bfhi(gv.x), bflo(gv.y), bfhi(gv.y)};
;         float yy[4];
; #pragma unroll
;         for (int j = 0; j < 4; ++j) yy[j] = px[j] * (acc[I][4 * rq + j] * invn1 + z1[j] * d1) * siluf(gt[j]);
;         uint2 ov; ov.x = pack2(yy[0], yy[1]); ov.y = pack2(yy[2], yy[3]);
;         *(uint2*)(dst + t4) = ov;
	ds_read_b64 v[160:161], v235 offset:128
	ds_read_b64 v[162:163], v235 offset:144
	ds_read_b64 v[164:165], v235 offset:160
	ds_read_b64 v[166:167], v235 offset:176
	v_and_b32_e32 v168, 0xffff0000, v88
	v_lshlrev_b32_e32 v169, 16, v89
	v_and_b32_e32 v170, 0xffff0000, v89
	v_lshlrev_b32_e32 v171, 16, v90
	v_and_b32_e32 v172, 0xffff0000, v90
	v_lshlrev_b32_e32 v173, 16, v91
	v_mul_f32_e32 v178, v83, v168
	v_fmac_f32_e32 v178, v82, v169
	v_fmac_f32_e32 v178, v80, v170
	v_add_f32_e32 v178, v70, v178
	v_mul_f32_e32 v179, v83, v169
	v_fmac_f32_e32 v179, v82, v170
	v_fmac_f32_e32 v179, v80, v171
	v_add_f32_e32 v179, v70, v179
	v_mul_f32_e32 v180, v83, v170
	v_fmac_f32_e32 v180, v82, v171
	v_fmac_f32_e32 v180, v80, v172
	v_add_f32_e32 v180, v70, v180
	v_mul_f32_e32 v181, v83, v171
	v_fmac_f32_e32 v181, v82, v172
	v_fmac_f32_e32 v181, v80, v173
	v_add_f32_e32 v181, v70, v181
	s_waitcnt lgkmcnt(0)
	v_lshlrev_b32_e32 v174, 16, v160
	v_and_b32_e32 v175, 0xffff0000, v160
	v_lshlrev_b32_e32 v176, 16, v161
	v_and_b32_e32 v177, 0xffff0000, v161
	v_mul_f32_e32 v174, v68, v174
	v_mul_f32_e32 v175, v68, v175
	v_mul_f32_e32 v176, v68, v176
	v_mul_f32_e32 v177, v68, v177
	v_fmac_f32_e32 v174, v238, v16
	v_fmac_f32_e32 v175, v238, v17
	v_fmac_f32_e32 v176, v238, v18
	v_fmac_f32_e32 v177, v238, v19
	v_mul_f32_e32 v174, v178, v174
	v_mul_f32_e32 v175, v179, v175
	v_mul_f32_e32 v176, v180, v176
	v_mul_f32_e32 v177, v181, v177
	v_lshlrev_b32_e32 v168, 16, v92
	v_and_b32_e32 v169, 0xffff0000, v92
	v_lshlrev_b32_e32 v170, 16, v93
	v_and_b32_e32 v171, 0xffff0000, v93
	v_mul_f32_e32 v178, 0xbfb8aa3b, v168
	v_mul_f32_e32 v179, 0xbfb8aa3b, v169
	v_mul_f32_e32 v180, 0xbfb8aa3b, v170
	v_mul_f32_e32 v181, 0xbfb8aa3b, v171
	v_exp_f32_e32 v178, v178
	v_exp_f32_e32 v179, v179
	v_exp_f32_e32 v180, v180
	v_exp_f32_e32 v181, v181
	v_add_f32_e32 v178, 1.0, v178
	v_add_f32_e32 v179, 1.0, v179
	v_add_f32_e32 v180, 1.0, v180
	v_add_f32_e32 v181, 1.0, v181
	v_rcp_f32_e32 v178, v178
	v_rcp_f32_e32 v179, v179
	v_rcp_f32_e32 v180, v180
	v_rcp_f32_e32 v181, v181
	v_mul_f32_e32 v178, v178, v168
	v_mul_f32_e32 v179, v179, v169
	v_mul_f32_e32 v180, v180, v170
	v_mul_f32_e32 v181, v181, v171
	v_mul_f32_e32 v174, v174, v178
	v_mul_f32_e32 v175, v175, v179
	v_mul_f32_e32 v176, v176, v180
	v_mul_f32_e32 v177, v177, v181
	v_cvt_pk_bf16_f32 v182, v174, v175
	v_cvt_pk_bf16_f32 v183, v176, v177
	global_store_dwordx2 v234, v[182:183], s[6:7] offset:128
	v_and_b32_e32 v168, 0xffff0000, v94
	v_lshlrev_b32_e32 v169, 16, v95
	v_and_b32_e32 v170, 0xffff0000, v95
	v_lshlrev_b32_e32 v171, 16, v96
	v_and_b32_e32 v172, 0xffff0000, v96
	v_lshlrev_b32_e32 v173, 16, v97
	v_mul_f32_e32 v178, v83, v168
	v_fmac_f32_e32 v178, v82, v169
	v_fmac_f32_e32 v178, v80, v170
	v_add_f32_e32 v178, v70, v178
	v_mul_f32_e32 v179, v83, v169
	v_fmac_f32_e32 v179, v82, v170
	v_fmac_f32_e32 v179, v80, v171
	v_add_f32_e32 v179, v70, v179
	v_mul_f32_e32 v180, v83, v170
	v_fmac_f32_e32 v180, v82, v171
	v_fmac_f32_e32 v180, v80, v172
	v_add_f32_e32 v180, v70, v180
	v_mul_f32_e32 v181, v83, v171
	v_fmac_f32_e32 v181, v82, v172
	v_fmac_f32_e32 v181, v80, v173
	v_add_f32_e32 v181, v70, v181
	v_lshlrev_b32_e32 v174, 16, v162
	v_and_b32_e32 v175, 0xffff0000, v162
	v_lshlrev_b32_e32 v176, 16, v163
	v_and_b32_e32 v177, 0xffff0000, v163
	v_mul_f32_e32 v174, v68, v174
	v_mul_f32_e32 v175, v68, v175
	v_mul_f32_e32 v176, v68, v176
	v_mul_f32_e32 v177, v68, v177
	v_fmac_f32_e32 v174, v238, v20
	v_fmac_f32_e32 v175, v238, v21
	v_fmac_f32_e32 v176, v238, v22
	v_fmac_f32_e32 v177, v238, v23
	v_mul_f32_e32 v174, v178, v174
	v_mul_f32_e32 v175, v179, v175
	v_mul_f32_e32 v176, v180, v176
	v_mul_f32_e32 v177, v181, v177
	v_lshlrev_b32_e32 v168, 16, v98
	v_and_b32_e32 v169, 0xffff0000, v98
	v_lshlrev_b32_e32 v170, 16, v99
	v_and_b32_e32 v171, 0xffff0000, v99
	v_mul_f32_e32 v178, 0xbfb8aa3b, v168
	v_mul_f32_e32 v179, 0xbfb8aa3b, v169
	v_mul_f32_e32 v180, 0xbfb8aa3b, v170
	v_mul_f32_e32 v181, 0xbfb8aa3b, v171
	v_exp_f32_e32 v178, v178
	v_exp_f32_e32 v179, v179
	v_exp_f32_e32 v180, v180
	v_exp_f32_e32 v181, v181
	v_add_f32_e32 v178, 1.0, v178
	v_add_f32_e32 v179, 1.0, v179
	v_add_f32_e32 v180, 1.0, v180
	v_add_f32_e32 v181, 1.0, v181
	v_rcp_f32_e32 v178, v178
	v_rcp_f32_e32 v179, v179
	v_rcp_f32_e32 v180, v180
	v_rcp_f32_e32 v181, v181
	v_mul_f32_e32 v178, v178, v168
	v_mul_f32_e32 v179, v179, v169
	v_mul_f32_e32 v180, v180, v170
	v_mul_f32_e32 v181, v181, v171
	v_mul_f32_e32 v174, v174, v178
	v_mul_f32_e32 v175, v175, v179
	v_mul_f32_e32 v176, v176, v180
	v_mul_f32_e32 v177, v177, v181
	v_cvt_pk_bf16_f32 v182, v174, v175
	v_cvt_pk_bf16_f32 v183, v176, v177
	global_store_dwordx2 v234, v[182:183], s[6:7] offset:144
	v_and_b32_e32 v168, 0xffff0000, v100
	v_lshlrev_b32_e32 v169, 16, v101
	v_and_b32_e32 v170, 0xffff0000, v101
	v_lshlrev_b32_e32 v171, 16, v102
	v_and_b32_e32 v172, 0xffff0000, v102
	v_lshlrev_b32_e32 v173, 16, v103
	v_mul_f32_e32 v178, v83, v168
	v_fmac_f32_e32 v178, v82, v169
	v_fmac_f32_e32 v178, v80, v170
	v_add_f32_e32 v178, v70, v178
	v_mul_f32_e32 v179, v83, v169
	v_fmac_f32_e32 v179, v82, v170
	v_fmac_f32_e32 v179, v80, v171
	v_add_f32_e32 v179, v70, v179
	v_mul_f32_e32 v180, v83, v170
	v_fmac_f32_e32 v180, v82, v171
	v_fmac_f32_e32 v180, v80, v172
	v_add_f32_e32 v180, v70, v180
	v_mul_f32_e32 v181, v83, v171
	v_fmac_f32_e32 v181, v82, v172
	v_fmac_f32_e32 v181, v80, v173
	v_add_f32_e32 v181, v70, v181
	v_lshlrev_b32_e32 v174, 16, v164
	v_and_b32_e32 v175, 0xffff0000, v164
	v_lshlrev_b32_e32 v176, 16, v165
	v_and_b32_e32 v177, 0xffff0000, v165
	v_mul_f32_e32 v174, v68, v174
	v_mul_f32_e32 v175, v68, v175
	v_mul_f32_e32 v176, v68, v176
; DI float bflo(unsigned v) { return __uint_as_float(v << 16); }
; DI float bfhi(unsigned v) { return __uint_as_float(v & 0xffff0000u); }
; DI float siluf(float x) { return x * __builtin_amdgcn_rcpf(1.f + __expf(-x)); }
; DI void hyena_item(const P& p, int l, int c, char* smem) {
;     ...
;       for (int rq = 0; rq < 4; ++rq) {
;         const int bq = 32 * I + 8 * rq + 4 * g;
;         const int t4 = 128 * a + bq;
;         float px[4];
;         sconv4(rowx, t4, x0, x1, x2, xb, px);
;         const uint2 zv = *(const uint2*)(U + (bt * 64 + a) * 136 + bq);
;         const uint2 gv = *(const uint2*)(rowg + t4);
;         const float z1[4] = {bflo(zv.x), bfhi(zv.x), bflo(zv.y), bfhi(zv.y)};
;         const float gt[4] = {bflo(gv.x), bfhi(gv.x), bflo(gv.y), bfhi(gv.y)};
;         float yy[4];
; #pragma unroll
;         for (int j = 0; j < 4; ++j) yy[j] = px[j] * (acc[I][4 * rq + j] * invn1 + z1[j] * d1) * siluf(gt[j]);
;         uint2 ov; ov.x = pack2(yy[0], yy[1]); ov.y = pack2(yy[2], yy[3]);
;         *(uint2*)(dst + t4) = ov;
	v_mul_f32_e32 v177, v68, v177
	v_fmac_f32_e32 v174, v238, v24
	v_fmac_f32_e32 v175, v238, v25
	v_fmac_f32_e32 v176, v238, v26
	v_fmac_f32_e32 v177, v238, v27
	v_mul_f32_e32 v174, v178, v174
	v_mul_f32_e32 v175, v179, v175
	v_mul_f32_e32 v176, v180, v176
	v_mul_f32_e32 v177, v181, v177
	v_lshlrev_b32_e32 v168, 16, v104
	v_and_b32_e32 v169, 0xffff0000, v104
	v_lshlrev_b32_e32 v170, 16, v105
	v_and_b32_e32 v171, 0xffff0000, v105
	v_mul_f32_e32 v178, 0xbfb8aa3b, v168
	v_mul_f32_e32 v179, 0xbfb8aa3b, v169
	v_mul_f32_e32 v180, 0xbfb8aa3b, v170
	v_mul_f32_e32 v181, 0xbfb8aa3b, v171
	v_exp_f32_e32 v178, v178
	v_exp_f32_e32 v179, v179
	v_exp_f32_e32 v180, v180
	v_exp_f32_e32 v181, v181
	v_add_f32_e32 v178, 1.0, v178
	v_add_f32_e32 v179, 1.0, v179
	v_add_f32_e32 v180, 1.0, v180
	v_add_f32_e32 v181, 1.0, v181
	v_rcp_f32_e32 v178, v178
	v_rcp_f32_e32 v179, v179
	v_rcp_f32_e32 v180, v180
	v_rcp_f32_e32 v181, v181
	v_mul_f32_e32 v178, v178, v168
	v_mul_f32_e32 v179, v179, v169
	v_mul_f32_e32 v180, v180, v170
	v_mul_f32_e32 v181, v181, v171
	v_mul_f32_e32 v174, v174, v178
	v_mul_f32_e32 v175, v175, v179
	v_mul_f32_e32 v176, v176, v180
	v_mul_f32_e32 v177, v177, v181
	v_cvt_pk_bf16_f32 v182, v174, v175
	v_cvt_pk_bf16_f32 v183, v176, v177
	global_store_dwordx2 v234, v[182:183], s[6:7] offset:160
	v_and_b32_e32 v168, 0xffff0000, v106
	v_lshlrev_b32_e32 v169, 16, v107
	v_and_b32_e32 v170, 0xffff0000, v107
	v_lshlrev_b32_e32 v171, 16, v108
	v_and_b32_e32 v172, 0xffff0000, v108
	v_lshlrev_b32_e32 v173, 16, v109
	v_mul_f32_e32 v178, v83, v168
	v_fmac_f32_e32 v178, v82, v169
	v_fmac_f32_e32 v178, v80, v170
	v_add_f32_e32 v178, v70, v178
	v_mul_f32_e32 v179, v83, v169
	v_fmac_f32_e32 v179, v82, v170
	v_fmac_f32_e32 v179, v80, v171
	v_add_f32_e32 v179, v70, v179
	v_mul_f32_e32 v180, v83, v170
	v_fmac_f32_e32 v180, v82, v171
	v_fmac_f32_e32 v180, v80, v172
	v_add_f32_e32 v180, v70, v180
	v_mul_f32_e32 v181, v83, v171
	v_fmac_f32_e32 v181, v82, v172
	v_fmac_f32_e32 v181, v80, v173
	v_add_f32_e32 v181, v70, v181
	v_lshlrev_b32_e32 v174, 16, v166
	v_and_b32_e32 v175, 0xffff0000, v166
	v_lshlrev_b32_e32 v176, 16, v167
	v_and_b32_e32 v177, 0xffff0000, v167
	v_mul_f32_e32 v174, v68, v174
	v_mul_f32_e32 v175, v68, v175
	v_mul_f32_e32 v176, v68, v176
	v_mul_f32_e32 v177, v68, v177
	v_fmac_f32_e32 v174, v238, v28
	v_fmac_f32_e32 v175, v238, v29
	v_fmac_f32_e32 v176, v238, v30
	v_fmac_f32_e32 v177, v238, v31
	v_mul_f32_e32 v174, v178, v174
	v_mul_f32_e32 v175, v179, v175
	v_mul_f32_e32 v176, v180, v176
	v_mul_f32_e32 v177, v181, v177
	v_lshlrev_b32_e32 v168, 16, v110
	v_and_b32_e32 v169, 0xffff0000, v110
	v_lshlrev_b32_e32 v170, 16, v111
	v_and_b32_e32 v171, 0xffff0000, v111
	v_mul_f32_e32 v178, 0xbfb8aa3b, v168
	v_mul_f32_e32 v179, 0xbfb8aa3b, v169
	v_mul_f32_e32 v180, 0xbfb8aa3b, v170
	v_mul_f32_e32 v181, 0xbfb8aa3b, v171
	v_exp_f32_e32 v178, v178
	v_exp_f32_e32 v179, v179
	v_exp_f32_e32 v180, v180
	v_exp_f32_e32 v181, v181
	v_add_f32_e32 v178, 1.0, v178
	v_add_f32_e32 v179, 1.0, v179
	v_add_f32_e32 v180, 1.0, v180
	v_add_f32_e32 v181, 1.0, v181
	v_rcp_f32_e32 v178, v178
	v_rcp_f32_e32 v179, v179
	v_rcp_f32_e32 v180, v180
	v_rcp_f32_e32 v181, v181
	v_mul_f32_e32 v178, v178, v168
	v_mul_f32_e32 v179, v179, v169
	v_mul_f32_e32 v180, v180, v170
	v_mul_f32_e32 v181, v181, v171
	v_mul_f32_e32 v174, v174, v178
	v_mul_f32_e32 v175, v175, v179
	v_mul_f32_e32 v176, v176, v180
	v_mul_f32_e32 v177, v177, v181
	v_cvt_pk_bf16_f32 v182, v174, v175
	v_cvt_pk_bf16_f32 v183, v176, v177
	global_store_dwordx2 v234, v[182:183], s[6:7] offset:176
	s_waitcnt vmcnt(4)
	ds_read_b64 v[160:161], v235 offset:192
	ds_read_b64 v[162:163], v235 offset:208
	ds_read_b64 v[164:165], v235 offset:224
	ds_read_b64 v[166:167], v235 offset:240
	v_and_b32_e32 v168, 0xffff0000, v112
	v_lshlrev_b32_e32 v169, 16, v113
	v_and_b32_e32 v170, 0xffff0000, v113
	v_lshlrev_b32_e32 v171, 16, v114
	v_and_b32_e32 v172, 0xffff0000, v114
	v_lshlrev_b32_e32 v173, 16, v115
	v_mul_f32_e32 v178, v83, v168
	v_fmac_f32_e32 v178, v82, v169
	v_fmac_f32_e32 v178, v80, v170
	v_add_f32_e32 v178, v70, v178
	v_mul_f32_e32 v179, v83, v169
	v_fmac_f32_e32 v179, v82, v170
	v_fmac_f32_e32 v179, v80, v171
	v_add_f32_e32 v179, v70, v179
	v_mul_f32_e32 v180, v83, v170
	v_fmac_f32_e32 v180, v82, v171
	v_fmac_f32_e32 v180, v80, v172
	v_add_f32_e32 v180, v70, v180
	v_mul_f32_e32 v181, v83, v171
	v_fmac_f32_e32 v181, v82, v172
	v_fmac_f32_e32 v181, v80, v173
	v_add_f32_e32 v181, v70, v181
	s_waitcnt lgkmcnt(0)
; DI float bflo(unsigned v) { return __uint_as_float(v << 16); }
; DI float bfhi(unsigned v) { return __uint_as_float(v & 0xffff0000u); }
; DI float siluf(float x) { return x * __builtin_amdgcn_rcpf(1.f + __expf(-x)); }
; DI void hyena_item(const P& p, int l, int c, char* smem) {
;     ...
;       for (int rq = 0; rq < 4; ++rq) {
;         const int bq = 32 * I + 8 * rq + 4 * g;
;         const int t4 = 128 * a + bq;
;         float px[4];
;         sconv4(rowx, t4, x0, x1, x2, xb, px);
;         const uint2 zv = *(const uint2*)(U + (bt * 64 + a) * 136 + bq);
;         const uint2 gv = *(const uint2*)(rowg + t4);
;         const float z1[4] = {bflo(zv.x), bfhi(zv.x), bflo(zv.y), bfhi(zv.y)};
;         const float gt[4] = {bflo(gv.x), bfhi(gv.x), bflo(gv.y), bfhi(gv.y)};
;         float yy[4];
; #pragma unroll
;         for (int j = 0; j < 4; ++j) yy[j] = px[j] * (acc[I][4 * rq + j] * invn1 + z1[j] * d1) * siluf(gt[j]);
;         uint2 ov; ov.x = pack2(yy[0], yy[1]); ov.y = pack2(yy[2], yy[3]);
;         *(uint2*)(dst + t4) = ov;
	v_lshlrev_b32_e32 v174, 16, v160
	v_and_b32_e32 v175, 0xffff0000, v160
	v_lshlrev_b32_e32 v176, 16, v161
	v_and_b32_e32 v177, 0xffff0000, v161
	v_mul_f32_e32 v174, v68, v174
	v_mul_f32_e32 v175, v68, v175
	v_mul_f32_e32 v176, v68, v176
	v_mul_f32_e32 v177, v68, v177
	v_fmac_f32_e32 v174, v238, v0
	v_fmac_f32_e32 v175, v238, v1
	v_fmac_f32_e32 v176, v238, v2
	v_fmac_f32_e32 v177, v238, v3
	v_mul_f32_e32 v174, v178, v174
	v_mul_f32_e32 v175, v179, v175
	v_mul_f32_e32 v176, v180, v176
	v_mul_f32_e32 v177, v181, v177
	v_lshlrev_b32_e32 v168, 16, v116
	v_and_b32_e32 v169, 0xffff0000, v116
	v_lshlrev_b32_e32 v170, 16, v117
	v_and_b32_e32 v171, 0xffff0000, v117
	v_mul_f32_e32 v178, 0xbfb8aa3b, v168
	v_mul_f32_e32 v179, 0xbfb8aa3b, v169
	v_mul_f32_e32 v180, 0xbfb8aa3b, v170
	v_mul_f32_e32 v181, 0xbfb8aa3b, v171
	v_exp_f32_e32 v178, v178
	v_exp_f32_e32 v179, v179
	v_exp_f32_e32 v180, v180
	v_exp_f32_e32 v181, v181
	v_add_f32_e32 v178, 1.0, v178
	v_add_f32_e32 v179, 1.0, v179
	v_add_f32_e32 v180, 1.0, v180
	v_add_f32_e32 v181, 1.0, v181
	v_rcp_f32_e32 v178, v178
	v_rcp_f32_e32 v179, v179
	v_rcp_f32_e32 v180, v180
	v_rcp_f32_e32 v181, v181
	v_mul_f32_e32 v178, v178, v168
	v_mul_f32_e32 v179, v179, v169
	v_mul_f32_e32 v180, v180, v170
	v_mul_f32_e32 v181, v181, v171
	v_mul_f32_e32 v174, v174, v178
	v_mul_f32_e32 v175, v175, v179
	v_mul_f32_e32 v176, v176, v180
	v_mul_f32_e32 v177, v177, v181
	v_cvt_pk_bf16_f32 v182, v174, v175
	v_cvt_pk_bf16_f32 v183, v176, v177
	global_store_dwordx2 v234, v[182:183], s[6:7] offset:192
	v_and_b32_e32 v168, 0xffff0000, v118
	v_lshlrev_b32_e32 v169, 16, v119
	v_and_b32_e32 v170, 0xffff0000, v119
	v_lshlrev_b32_e32 v171, 16, v120
	v_and_b32_e32 v172, 0xffff0000, v120
	v_lshlrev_b32_e32 v173, 16, v121
	v_mul_f32_e32 v178, v83, v168
	v_fmac_f32_e32 v178, v82, v169
	v_fmac_f32_e32 v178, v80, v170
	v_add_f32_e32 v178, v70, v178
	v_mul_f32_e32 v179, v83, v169
	v_fmac_f32_e32 v179, v82, v170
	v_fmac_f32_e32 v179, v80, v171
	v_add_f32_e32 v179, v70, v179
	v_mul_f32_e32 v180, v83, v170
	v_fmac_f32_e32 v180, v82, v171
	v_fmac_f32_e32 v180, v80, v172
	v_add_f32_e32 v180, v70, v180
	v_mul_f32_e32 v181, v83, v171
	v_fmac_f32_e32 v181, v82, v172
	v_fmac_f32_e32 v181, v80, v173
	v_add_f32_e32 v181, v70, v181
	v_lshlrev_b32_e32 v174, 16, v162
	v_and_b32_e32 v175, 0xffff0000, v162
	v_lshlrev_b32_e32 v176, 16, v163
	v_and_b32_e32 v177, 0xffff0000, v163
	v_mul_f32_e32 v174, v68, v174
	v_mul_f32_e32 v175, v68, v175
	v_mul_f32_e32 v176, v68, v176
	v_mul_f32_e32 v177, v68, v177
	v_fmac_f32_e32 v174, v238, v4
	v_fmac_f32_e32 v175, v238, v5
	v_fmac_f32_e32 v176, v238, v6
	v_fmac_f32_e32 v177, v238, v7
	v_mul_f32_e32 v174, v178, v174
	v_mul_f32_e32 v175, v179, v175
	v_mul_f32_e32 v176, v180, v176
	v_mul_f32_e32 v177, v181, v177
	v_lshlrev_b32_e32 v168, 16, v122
	v_and_b32_e32 v169, 0xffff0000, v122
	v_lshlrev_b32_e32 v170, 16, v123
	v_and_b32_e32 v171, 0xffff0000, v123
	v_mul_f32_e32 v178, 0xbfb8aa3b, v168
	v_mul_f32_e32 v179, 0xbfb8aa3b, v169
	v_mul_f32_e32 v180, 0xbfb8aa3b, v170
	v_mul_f32_e32 v181, 0xbfb8aa3b, v171
	v_exp_f32_e32 v178, v178
	v_exp_f32_e32 v179, v179
	v_exp_f32_e32 v180, v180
	v_exp_f32_e32 v181, v181
	v_add_f32_e32 v178, 1.0, v178
	v_add_f32_e32 v179, 1.0, v179
	v_add_f32_e32 v180, 1.0, v180
	v_add_f32_e32 v181, 1.0, v181
	v_rcp_f32_e32 v178, v178
	v_rcp_f32_e32 v179, v179
	v_rcp_f32_e32 v180, v180
	v_rcp_f32_e32 v181, v181
	v_mul_f32_e32 v178, v178, v168
	v_mul_f32_e32 v179, v179, v169
	v_mul_f32_e32 v180, v180, v170
	v_mul_f32_e32 v181, v181, v171
	v_mul_f32_e32 v174, v174, v178
	v_mul_f32_e32 v175, v175, v179
	v_mul_f32_e32 v176, v176, v180
	v_mul_f32_e32 v177, v177, v181
	v_cvt_pk_bf16_f32 v182, v174, v175
	v_cvt_pk_bf16_f32 v183, v176, v177
	global_store_dwordx2 v234, v[182:183], s[6:7] offset:208
	v_and_b32_e32 v168, 0xffff0000, v124
	v_lshlrev_b32_e32 v169, 16, v125
	v_and_b32_e32 v170, 0xffff0000, v125
	v_lshlrev_b32_e32 v171, 16, v126
	v_and_b32_e32 v172, 0xffff0000, v126
	v_lshlrev_b32_e32 v173, 16, v127
	v_mul_f32_e32 v178, v83, v168
	v_fmac_f32_e32 v178, v82, v169
	v_fmac_f32_e32 v178, v80, v170
	v_add_f32_e32 v178, v70, v178
	v_mul_f32_e32 v179, v83, v169
	v_fmac_f32_e32 v179, v82, v170
; DI float bf2f(unsigned v) { return __uint_as_float(v << 16); }
; DI float bflo(unsigned v) { return __uint_as_float(v << 16); }
; DI float bfhi(unsigned v) { return __uint_as_float(v & 0xffff0000u); }
; DI float siluf(float x) { return x * __builtin_amdgcn_rcpf(1.f + __expf(-x)); }
; DI void sconv4(const u16* row, int t4, float w0, float w1, float w2, float bias, float (&o)[4]) {
;     ...
;   const float xp = (t4 + 4 < SEQ) ? bf2f(row[t4 + 4]) : 0.f;
; DI void hyena_item(const P& p, int l, int c, char* smem) {
;     ...
;       for (int rq = 0; rq < 4; ++rq) {
;         const int bq = 32 * I + 8 * rq + 4 * g;
;         const int t4 = 128 * a + bq;
;         float px[4];
;         sconv4(rowx, t4, x0, x1, x2, xb, px);
;         const uint2 zv = *(const uint2*)(U + (bt * 64 + a) * 136 + bq);
;         const uint2 gv = *(const uint2*)(rowg + t4);
;         const float z1[4] = {bflo(zv.x), bfhi(zv.x), bflo(zv.y), bfhi(zv.y)};
;         const float gt[4] = {bflo(gv.x), bfhi(gv.x), bflo(gv.y), bfhi(gv.y)};
;         float yy[4];
; #pragma unroll
;         for (int j = 0; j < 4; ++j) yy[j] = px[j] * (acc[I][4 * rq + j] * invn1 + z1[j] * d1) * siluf(gt[j]);
;         uint2 ov; ov.x = pack2(yy[0], yy[1]); ov.y = pack2(yy[2], yy[3]);
;         *(uint2*)(dst + t4) = ov;
	v_fmac_f32_e32 v179, v80, v171
	v_add_f32_e32 v179, v70, v179
	v_mul_f32_e32 v180, v83, v170
	v_fmac_f32_e32 v180, v82, v171
	v_fmac_f32_e32 v180, v80, v172
	v_add_f32_e32 v180, v70, v180
	v_mul_f32_e32 v181, v83, v171
	v_fmac_f32_e32 v181, v82, v172
	v_fmac_f32_e32 v181, v80, v173
	v_add_f32_e32 v181, v70, v181
	v_lshlrev_b32_e32 v174, 16, v164
	v_and_b32_e32 v175, 0xffff0000, v164
	v_lshlrev_b32_e32 v176, 16, v165
	v_and_b32_e32 v177, 0xffff0000, v165
	v_mul_f32_e32 v174, v68, v174
	v_mul_f32_e32 v175, v68, v175
	v_mul_f32_e32 v176, v68, v176
	v_mul_f32_e32 v177, v68, v177
	v_fmac_f32_e32 v174, v238, v8
	v_fmac_f32_e32 v175, v238, v9
	v_fmac_f32_e32 v176, v238, v10
	v_fmac_f32_e32 v177, v238, v11
	v_mul_f32_e32 v174, v178, v174
	v_mul_f32_e32 v175, v179, v175
	v_mul_f32_e32 v176, v180, v176
	v_mul_f32_e32 v177, v181, v177
	v_lshlrev_b32_e32 v168, 16, v128
	v_and_b32_e32 v169, 0xffff0000, v128
	v_lshlrev_b32_e32 v170, 16, v129
	v_and_b32_e32 v171, 0xffff0000, v129
	v_mul_f32_e32 v178, 0xbfb8aa3b, v168
	v_mul_f32_e32 v179, 0xbfb8aa3b, v169
	v_mul_f32_e32 v180, 0xbfb8aa3b, v170
	v_mul_f32_e32 v181, 0xbfb8aa3b, v171
	v_exp_f32_e32 v178, v178
	v_exp_f32_e32 v179, v179
	v_exp_f32_e32 v180, v180
	v_exp_f32_e32 v181, v181
	v_add_f32_e32 v178, 1.0, v178
	v_add_f32_e32 v179, 1.0, v179
	v_add_f32_e32 v180, 1.0, v180
	v_add_f32_e32 v181, 1.0, v181
	v_rcp_f32_e32 v178, v178
	v_rcp_f32_e32 v179, v179
	v_rcp_f32_e32 v180, v180
	v_rcp_f32_e32 v181, v181
	v_mul_f32_e32 v178, v178, v168
	v_mul_f32_e32 v179, v179, v169
	v_mul_f32_e32 v180, v180, v170
	v_mul_f32_e32 v181, v181, v171
	v_mul_f32_e32 v174, v174, v178
	v_mul_f32_e32 v175, v175, v179
	v_mul_f32_e32 v176, v176, v180
	v_mul_f32_e32 v177, v177, v181
	v_cvt_pk_bf16_f32 v182, v174, v175
	v_cvt_pk_bf16_f32 v183, v176, v177
	global_store_dwordx2 v234, v[182:183], s[6:7] offset:224
	v_cmp_ne_u32_e32 vcc, 0x1f84, v233
	s_nop 1
	v_and_b32_e32 v168, 0xffff0000, v130
	v_lshlrev_b32_e32 v169, 16, v131
	v_and_b32_e32 v170, 0xffff0000, v131
	v_lshlrev_b32_e32 v171, 16, v132
	v_and_b32_e32 v172, 0xffff0000, v132
	v_lshlrev_b32_e32 v173, 16, v133
	v_cndmask_b32_e32 v173, 0, v173, vcc
	v_mul_f32_e32 v178, v83, v168
	v_fmac_f32_e32 v178, v82, v169
	v_fmac_f32_e32 v178, v80, v170
	v_add_f32_e32 v178, v70, v178
	v_mul_f32_e32 v179, v83, v169
	v_fmac_f32_e32 v179, v82, v170
	v_fmac_f32_e32 v179, v80, v171
	v_add_f32_e32 v179, v70, v179
	v_mul_f32_e32 v180, v83, v170
	v_fmac_f32_e32 v180, v82, v171
	v_fmac_f32_e32 v180, v80, v172
	v_add_f32_e32 v180, v70, v180
	v_mul_f32_e32 v181, v83, v171
	v_fmac_f32_e32 v181, v82, v172
	v_fmac_f32_e32 v181, v80, v173
	v_add_f32_e32 v181, v70, v181
	v_lshlrev_b32_e32 v174, 16, v166
	v_and_b32_e32 v175, 0xffff0000, v166
	v_lshlrev_b32_e32 v176, 16, v167
	v_and_b32_e32 v177, 0xffff0000, v167
	v_mul_f32_e32 v174, v68, v174
	v_mul_f32_e32 v175, v68, v175
	v_mul_f32_e32 v176, v68, v176
	v_mul_f32_e32 v177, v68, v177
	v_fmac_f32_e32 v174, v238, v12
	v_fmac_f32_e32 v175, v238, v13
	v_fmac_f32_e32 v176, v238, v14
	v_fmac_f32_e32 v177, v238, v15
	v_mul_f32_e32 v174, v178, v174
	v_mul_f32_e32 v175, v179, v175
	v_mul_f32_e32 v176, v180, v176
	v_mul_f32_e32 v177, v181, v177
	v_lshlrev_b32_e32 v168, 16, v134
	v_and_b32_e32 v169, 0xffff0000, v134
	v_lshlrev_b32_e32 v170, 16, v135
	v_and_b32_e32 v171, 0xffff0000, v135
	v_mul_f32_e32 v178, 0xbfb8aa3b, v168
	v_mul_f32_e32 v179, 0xbfb8aa3b, v169
	v_mul_f32_e32 v180, 0xbfb8aa3b, v170
	v_mul_f32_e32 v181, 0xbfb8aa3b, v171
	v_exp_f32_e32 v178, v178
	v_exp_f32_e32 v179, v179
	v_exp_f32_e32 v180, v180
	v_exp_f32_e32 v181, v181
	v_add_f32_e32 v178, 1.0, v178
	v_add_f32_e32 v179, 1.0, v179
	v_add_f32_e32 v180, 1.0, v180
	v_add_f32_e32 v181, 1.0, v181
	v_rcp_f32_e32 v178, v178
	v_rcp_f32_e32 v179, v179
	v_rcp_f32_e32 v180, v180
	v_rcp_f32_e32 v181, v181
	v_mul_f32_e32 v178, v178, v168
	v_mul_f32_e32 v179, v179, v169
	v_mul_f32_e32 v180, v180, v170
	v_mul_f32_e32 v181, v181, v171
	v_mul_f32_e32 v174, v174, v178
	v_mul_f32_e32 v175, v175, v179
	v_mul_f32_e32 v176, v176, v180
	v_mul_f32_e32 v177, v177, v181
	v_cvt_pk_bf16_f32 v182, v174, v175
	v_cvt_pk_bf16_f32 v183, v176, v177
	global_store_dwordx2 v234, v[182:183], s[6:7] offset:240
